# Order::next per-tile index math: group size is provably 8 for the FFN-up and output GEMM phases, so the v_rcp/readfirstlane integer-division chain is replaced by shift/and (on top of peeled K-loops)
# baseline (speedup 1.0000x reference)
.LBB0_450:
	s_add_i32 s71, s71, 1
	s_mul_i32 s20, s71, s84
	s_mul_hi_u32 s21, s71, s34
	s_add_i32 s21, s21, s20
	s_mul_i32 s20, s71, s34
	s_add_u32 s28, s20, s2
	s_addc_u32 s29, s21, s83
	v_mov_b64_e32 v[10:11], 0xb00
	v_cmp_lt_i64_e64 s[20:21], s[28:29], v[10:11]
	v_mov_b64_e32 v[10:11], 0xaff
	v_cmp_gt_i64_e32 vcc, s[28:29], v[10:11]
	s_cbranch_vccnz .LBB0_452
	s_ashr_i32 s29, s28, 31
	s_lshr_b32 s29, s29, 29
	s_add_i32 s29, s28, s29
	s_ashr_i32 s30, s29, 3
	s_and_b32 s29, s29, -8
	s_sub_i32 s28, s28, s29
	s_cmp_lt_i32 s28, 0
	s_movk_i32 s29, 0x161
	s_cselect_b32 s29, s29, 0x160
	s_mul_i32 s28, s28, s29
	s_add_i32 s28, s28, s30
	s_mul_hi_i32 s29, s28, 0x2e8ba2e9
	s_lshr_b32 s30, s29, 31
	s_ashr_i32 s29, s29, 5
	s_add_i32 s29, s29, s30
	s_lshl_b32 s30, s29, 3
	s_mulk_i32 s29, 0xb0
	s_sub_i32 s28, s28, s29
	s_lshr_b32 s72, s28, 3
	s_and_b32 s28, s28, 7
	s_add_i32 s74, s30, s28
	s_lshl_b32 s98, s74, 8
	s_lshl_b32 s80, s72, 8

.LBB0_1059:
	s_ashr_i32 s8, s24, 3
	s_add_i32 s8, s28, s8
	s_ashr_i32 s9, s8, 31
	s_lshr_b32 s9, s9, 27
	s_add_i32 s9, s8, s9
	s_ashr_i32 s24, s9, 5
	s_lshl_b32 s24, s24, 3
	s_andn2_b32 s9, s9, 31
	s_sub_i32 s8, s8, s9
	s_lshr_b32 s81, s8, 3
	s_and_b32 s8, s8, 7
	s_add_i32 s90, s24, s8
	s_lshl_b32 s87, s90, 8
	s_lshl_b32 s86, s81, 8
